# phase-0 weight transposes with folded norm gain: 8 weight + 8 gain loads batched per iteration instead of load-wait-multiply per row
# baseline (speedup 1.0000x reference)
; __device__ __forceinline__ void transpose_item(const float* W, const float* gain, int K, int N, bf16_t* WT, int mode, LAS float* scr, int item, int lane) {
;     ...
; #pragma unroll 8
;     for (int i = 0; i < 32; ++i) { const int kk = 2 * i + (lane >> 5); const float g = gain ? gain[k0 + kk] : 1.0f; scr[kk * 33 + (lane & 31)] = W[(size_t)(k0 + kk) * N + n0 + (lane & 31)] * g; }
.LBB0_618:
	s_andn2_b64 vcc, exec, s[20:21]
	s_cbranch_vccnz .Ltga_nogain
	v_lshl_add_u64 v[112:113], s[22:23], 0, v[0:1]
	global_load_dword v80, v[112:113], off
	v_lshl_add_u64 v[114:115], s[22:23], 0, v[18:19]
	global_load_dword v81, v[114:115], off offset:8
	global_load_dword v82, v[114:115], off offset:16
	global_load_dword v83, v[114:115], off offset:24
	global_load_dword v84, v[114:115], off offset:32
	global_load_dword v85, v[114:115], off offset:40
	global_load_dword v86, v[114:115], off offset:48
	global_load_dword v87, v[114:115], off offset:56
	s_branch .Ltga_w
.Ltga_nogain:
	v_mov_b32_e32 v80, 1.0
	v_mov_b32_e32 v81, 1.0
	v_mov_b32_e32 v82, 1.0
	v_mov_b32_e32 v83, 1.0
	v_mov_b32_e32 v84, 1.0
	v_mov_b32_e32 v85, 1.0
	v_mov_b32_e32 v86, 1.0
	v_mov_b32_e32 v87, 1.0
.Ltga_w:
	v_lshl_add_u64 v[96:97], v[32:33], 0, s[8:9]
	global_load_dword v88, v[96:97], off
	v_lshl_add_u64 v[98:99], v[30:31], 0, s[8:9]
	global_load_dword v89, v[98:99], off
	v_lshl_add_u64 v[100:101], v[28:29], 0, s[8:9]
	global_load_dword v90, v[100:101], off
	v_lshl_add_u64 v[102:103], v[26:27], 0, s[8:9]
	global_load_dword v91, v[102:103], off
	v_lshl_add_u64 v[104:105], v[24:25], 0, s[8:9]
	global_load_dword v92, v[104:105], off
	v_lshl_add_u64 v[106:107], v[22:23], 0, s[8:9]
	global_load_dword v93, v[106:107], off
	v_lshl_add_u64 v[108:109], v[20:21], 0, s[8:9]
	global_load_dword v94, v[108:109], off
	v_lshl_add_u64 v[110:111], v[16:17], 0, s[8:9]
	global_load_dword v95, v[110:111], off
	s_waitcnt vmcnt(0)
	v_mul_f32_e32 v88, v80, v88
	v_mul_f32_e32 v89, v81, v89
	v_mul_f32_e32 v90, v82, v90
	v_mul_f32_e32 v91, v83, v91
	v_mul_f32_e32 v92, v84, v92
	v_mul_f32_e32 v93, v85, v93
	v_mul_f32_e32 v94, v86, v94
	v_mul_f32_e32 v95, v87, v95
	ds_write_b32 v7, v88
	ds_write_b32 v7, v89 offset:264
	ds_write_b32 v7, v90 offset:528
	ds_write_b32 v7, v91 offset:792
	ds_write_b32 v7, v92 offset:1056
	ds_write_b32 v7, v93 offset:1320
	ds_write_b32 v7, v94 offset:1584
	ds_write_b32 v7, v95 offset:1848
	s_add_u32 s8, s8, 0x2c000
	s_addc_u32 s9, s9, 0
	s_add_u32 s22, s22, 64
	s_addc_u32 s23, s23, 0
	v_add_u32_e32 v7, 0x840, v7
	s_cmp_lg_u32 s8, 0xb0000
	s_cbranch_scc1 .LBB0_618

; __device__ __forceinline__ void transpose_item(const float* W, const float* gain, int K, int N, bf16_t* WT, int mode, LAS float* scr, int item, int lane) {
;     ...
;     for (int i = 0; i < 32; ++i) { const int kk = 2 * i + (lane >> 5); const float g = gain ? gain[k0 + kk] : 1.0f; scr[kk * 33 + (lane & 31)] = W[(size_t)(k0 + kk) * N + n0 + (lane & 31)] * g; }
.LBB0_639:
	s_andn2_b64 vcc, exec, s[20:21]
	s_cbranch_vccnz .Ltgb_nogain
	v_lshl_add_u64 v[112:113], s[0:1], 0, v[0:1]
	global_load_dword v80, v[112:113], off
	v_lshl_add_u64 v[114:115], s[0:1], 0, v[18:19]
	global_load_dword v81, v[114:115], off offset:8
	global_load_dword v82, v[114:115], off offset:16
	global_load_dword v83, v[114:115], off offset:24
	global_load_dword v84, v[114:115], off offset:32
	global_load_dword v85, v[114:115], off offset:40
	global_load_dword v86, v[114:115], off offset:48
	global_load_dword v87, v[114:115], off offset:56
	s_branch .Ltgb_w

; __device__ __forceinline__ void transpose_item(const float* W, const float* gain, int K, int N, bf16_t* WT, int mode, LAS float* scr, int item, int lane) {
;     ...
;     for (int i = 0; i < 32; ++i) { const int kk = 2 * i + (lane >> 5); const float g = gain ? gain[k0 + kk] : 1.0f; scr[kk * 33 + (lane & 31)] = W[(size_t)(k0 + kk) * N + n0 + (lane & 31)] * g; }
.Ltgb_w:
	v_lshl_add_u64 v[96:97], v[32:33], 0, s[8:9]
	global_load_dword v88, v[96:97], off
	v_lshl_add_u64 v[98:99], v[30:31], 0, s[8:9]
	global_load_dword v89, v[98:99], off
	v_lshl_add_u64 v[100:101], v[28:29], 0, s[8:9]
	global_load_dword v90, v[100:101], off
	v_lshl_add_u64 v[102:103], v[26:27], 0, s[8:9]
	global_load_dword v91, v[102:103], off
	v_lshl_add_u64 v[104:105], v[24:25], 0, s[8:9]
	global_load_dword v92, v[104:105], off
	v_lshl_add_u64 v[106:107], v[22:23], 0, s[8:9]
	global_load_dword v93, v[106:107], off
	v_lshl_add_u64 v[108:109], v[20:21], 0, s[8:9]
	global_load_dword v94, v[108:109], off
	v_lshl_add_u64 v[110:111], v[16:17], 0, s[8:9]
	global_load_dword v95, v[110:111], off
	s_waitcnt vmcnt(0)
	v_mul_f32_e32 v88, v80, v88
	v_mul_f32_e32 v89, v81, v89
	v_mul_f32_e32 v90, v82, v90
	v_mul_f32_e32 v91, v83, v91
	v_mul_f32_e32 v92, v84, v92
	v_mul_f32_e32 v93, v85, v93
	v_mul_f32_e32 v94, v86, v94
	v_mul_f32_e32 v95, v87, v95
	ds_write_b32 v7, v88
	ds_write_b32 v7, v89 offset:264
	ds_write_b32 v7, v90 offset:528
	ds_write_b32 v7, v91 offset:792
	ds_write_b32 v7, v92 offset:1056
	ds_write_b32 v7, v93 offset:1320
	ds_write_b32 v7, v94 offset:1584
	ds_write_b32 v7, v95 offset:1848
	s_add_u32 s8, s8, 0x2c000
	s_addc_u32 s9, s9, 0
	s_add_u32 s0, s0, 64
	s_addc_u32 s1, s1, 0
	v_add_u32_e32 v7, 0x840, v7
	s_cmp_lg_u32 s8, 0xb0000
	s_cbranch_scc1 .LBB0_639

; __device__ __forceinline__ void transpose_item(const float* W, const float* gain, int K, int N, bf16_t* WT, int mode, LAS float* scr, int item, int lane) {
;     ...
;     for (int i = 0; i < 32; ++i) { const int kk = 2 * i + (lane >> 5); const float g = gain ? gain[k0 + kk] : 1.0f; scr[kk * 33 + (lane & 31)] = W[(size_t)(k0 + kk) * N + n0 + (lane & 31)] * g; }
.LBB0_664:
	s_andn2_b64 vcc, exec, s[22:23]
	s_cbranch_vccnz .Ltgc_nogain
	v_lshl_add_u64 v[112:113], s[8:9], 0, v[34:35]
	global_load_dword v80, v[112:113], off
	v_lshl_add_u64 v[114:115], s[8:9], 0, v[18:19]
	global_load_dword v81, v[114:115], off offset:8
	global_load_dword v82, v[114:115], off offset:16
	global_load_dword v83, v[114:115], off offset:24
	global_load_dword v84, v[114:115], off offset:32
	global_load_dword v85, v[114:115], off offset:40
	global_load_dword v86, v[114:115], off offset:48
	global_load_dword v87, v[114:115], off offset:56
	s_branch .Ltgc_w

; __device__ __forceinline__ void transpose_item(const float* W, const float* gain, int K, int N, bf16_t* WT, int mode, LAS float* scr, int item, int lane) {
;     ...
;     for (int i = 0; i < 32; ++i) { const int kk = 2 * i + (lane >> 5); const float g = gain ? gain[k0 + kk] : 1.0f; scr[kk * 33 + (lane & 31)] = W[(size_t)(k0 + kk) * N + n0 + (lane & 31)] * g; }
.Ltgc_w:
	v_lshl_add_u64 v[96:97], v[32:33], 0, s[20:21]
	global_load_dword v88, v[96:97], off
	v_lshl_add_u64 v[98:99], v[30:31], 0, s[20:21]
	global_load_dword v89, v[98:99], off
	v_lshl_add_u64 v[100:101], v[28:29], 0, s[20:21]
	global_load_dword v90, v[100:101], off
	v_lshl_add_u64 v[102:103], v[26:27], 0, s[20:21]
	global_load_dword v91, v[102:103], off
	v_lshl_add_u64 v[104:105], v[24:25], 0, s[20:21]
	global_load_dword v92, v[104:105], off
	v_lshl_add_u64 v[106:107], v[22:23], 0, s[20:21]
	global_load_dword v93, v[106:107], off
	v_lshl_add_u64 v[108:109], v[20:21], 0, s[20:21]
	global_load_dword v94, v[108:109], off
	v_lshl_add_u64 v[110:111], v[16:17], 0, s[20:21]
	global_load_dword v95, v[110:111], off
	s_waitcnt vmcnt(0)
	v_mul_f32_e32 v88, v80, v88
	v_mul_f32_e32 v89, v81, v89
	v_mul_f32_e32 v90, v82, v90
	v_mul_f32_e32 v91, v83, v91
	v_mul_f32_e32 v92, v84, v92
	v_mul_f32_e32 v93, v85, v93
	v_mul_f32_e32 v94, v86, v94
	v_mul_f32_e32 v95, v87, v95
	ds_write_b32 v0, v88
	ds_write_b32 v0, v89 offset:264
	ds_write_b32 v0, v90 offset:528
	ds_write_b32 v0, v91 offset:792
	ds_write_b32 v0, v92 offset:1056
	ds_write_b32 v0, v93 offset:1320
	ds_write_b32 v0, v94 offset:1584
	ds_write_b32 v0, v95 offset:1848
	s_add_u32 s20, s20, 0x30000
	s_addc_u32 s21, s21, 0
	s_add_u32 s8, s8, 64
	s_addc_u32 s9, s9, 0
	v_add_u32_e32 v0, 0x840, v0
	s_cmp_lg_u32 s20, 0xc0000
	s_cbranch_scc1 .LBB0_664
	s_branch .LBB0_605
